# queue grouping of 16 q-blocks per head (variant of v22)
# speedup vs baseline: 1.0371x; 1.0097x over previous
; DI void phase2(const Params& p, char* smem, const int g_wave) {
;     ...
;       int qb, bh;
;       if (prm) { int a = it - N0; qb = 31 - (a >> 6); bh = a & 63; } else { qb = 0; bh = it - N2; }
;       const int b = bh >> 3, h = bh & 7;
;       const size_t rowq = prm ? (size_t)b * 8192 + qb * 256 : (size_t)TP + b * 64;
.LBB0_692:
	s_add_i32 s4, s6, 0xffffff80
	s_lshr_b32 s5, s4, 10
	s_lshl_b32 s5, s5, 4
	s_and_b32 s50, s4, 15
	s_add_i32 s5, s5, s50
	s_sub_i32 s78, 31, s5
	s_bfe_u32 s50, s4, 0x60004
